# moba gather: batch K ds_reads for tiles 0-2 and prefetch V ds_reads for tiles 1,3 into free registers (counted lgkmcnt)
# speedup vs baseline: 1.0045x; 1.0045x over previous
; DI void qk_tile(const u16* Ks, const bf16x8* qf, f32x16* s, int rl, int hh) {
; #pragma unroll
;   for (int kb = 0; kb < 2; ++kb) {
; #pragma unroll
;     for (int i = 0; i < 16; ++i) s[kb][i] = 0.f;
; #pragma unroll
;     for (int ks = 0; ks < 4; ++ks) {
;       bf16x8 a = *(const bf16x8*)(Ks + (kb * 32 + rl) * KVS + ks * 16 + hh * 8);
;       s[kb] = MFMA32(a, qf[ks], s[kb]);
;     }
;   }
; }
; DI void pv_tile(const u16* Vs, const f32x16* s, f32x16* o, int rl, int hh) {
; #pragma unroll
;   for (int kk = 0; kk < 4; ++kk) {
;     const int kb = kk >> 1, i0 = 8 * (kk & 1);
;     bf16x8 pf = pack8(s[kb][i0], s[kb][i0 + 1], s[kb][i0 + 2], s[kb][i0 + 3], s[kb][i0 + 4], s[kb][i0 + 5], s[kb][i0 + 6], s[kb][i0 + 7]);
; #pragma unroll
;     for (int db = 0; db < 2; ++db) {
;       const u16* vp = Vs + (db * 32 + rl) * KVS + kk * 16 + hh * 4;
;       s16x4 lo = *(const s16x4*)vp, hi = *(const s16x4*)(vp + 8);
;       bf16x8 a = __builtin_shufflevector(lo, hi, 0, 1, 2, 3, 4, 5, 6, 7);
;       o[db] = MFMA32(a, pf, o[db]);
;     }
;   }
; }
; DI float fexp2(float x) { return __builtin_amdgcn_exp2f(x); }
; template <int MODE>
; DI void osm(f32x16* s, uint32_t vm, float& m, float& l, f32x16* o) {
;   float mx = -1e30f;
; #pragma unroll
;   for (int kb = 0; kb < 2; ++kb)
; #pragma unroll
;     for (int i = 0; i < 16; ++i) {
;       if (MODE == 2) s[kb][i] = ((vm >> (kb * 16 + i)) & 1u) ? s[kb][i] : -1e30f;
;       mx = fmaxf(mx, s[kb][i]);
;     }
;   mx *= SCL2;
;   if (MODE == 1) mx = vm ? mx : -1e30f;
;   mx = xmax32(mx);
;   const float mn = fmaxf(m, mx);
;   const float alpha = fexp2(m - mn);
;   const bool rowok = (MODE == 1) ? (vm != 0u) : true;
; DI bf16x8 rope_frag(bf16x8 f, const float* cs  , int hh) {
;   u32x4 w = __builtin_bit_cast(u32x4, f), ow;
; #pragma unroll
;   for (int q = 0; q < 4; ++q) ow[q] = shxi<32>((int)w[q]);
;   float mine[8], oth[8], res[8];
; #pragma unroll
;   for (int q = 0; q < 4; ++q) {
;     mine[2 * q] = bflo(w[q]); mine[2 * q + 1] = bfhi(w[q]);
;     oth[2 * q] = bflo(ow[q]); oth[2 * q + 1] = bfhi(ow[q]);
;   }
;   const float sg = hh ? 1.f : -1.f;
; #pragma unroll
;   for (int i = 0; i < 8; ++i) res[i] = mine[i] * cs[i] + sg * oth[i] * cs[8 + i];
;   u32x4 r = {pack2(res[0], res[1]), pack2(res[2], res[3]), pack2(res[4], res[5]), pack2(res[6], res[7])};
;   return __builtin_bit_cast(bf16x8, r);
; }
.LBB0_744:
	v_xor_b32_e32 v20, v21, v20
	v_xor_b32_sdwa v28, v20, v0 dst_sel:WORD_1 dst_unused:UNUSED_PAD src0_sel:DWORD src1_sel:DWORD
	v_xor_b32_e32 v21, v23, v22
	v_xor_b32_e32 v22, v25, v24
	v_xor_b32_e32 v23, v27, v26
	v_bitop3_b32 v26, v20, s3, v0 bitop3:0x48
	v_xor_b32_sdwa v24, v22, v2 dst_sel:WORD_1 dst_unused:UNUSED_PAD src0_sel:DWORD src1_sel:DWORD
	v_xor_b32_sdwa v25, v23, v3 dst_sel:WORD_1 dst_unused:UNUSED_PAD src0_sel:DWORD src1_sel:DWORD
	v_bitop3_b32 v30, v22, s3, v2 bitop3:0x48
	v_bitop3_b32 v31, v23, s3, v3 bitop3:0x48
	v_cndmask_b32_e64 v23, v26, -v26, s[10:11]
	v_cndmask_b32_e64 v22, v28, -v28, s[10:11]
	v_xor_b32_sdwa v29, v21, v1 dst_sel:WORD_1 dst_unused:UNUSED_PAD src0_sel:DWORD src1_sel:DWORD
	v_bitop3_b32 v27, v21, s3, v1 bitop3:0x48
	v_lshlrev_b32_e32 v20, 16, v0
	v_and_b32_e32 v21, 0xffff0000, v0
	s_waitcnt vmcnt(9)
	v_pk_mul_f32 v[12:13], v[12:13], v[22:23]
	v_lshlrev_b32_e32 v0, 16, v1
	s_waitcnt vmcnt(9)
	v_pk_fma_f32 v[12:13], v[16:17], v[20:21], v[12:13]
	v_cndmask_b32_e64 v17, v27, -v27, s[10:11]
	v_cndmask_b32_e64 v16, v29, -v29, s[10:11]
	v_and_b32_e32 v1, 0xffff0000, v1
	v_pk_mul_f32 v[14:15], v[16:17], v[14:15]
	v_cndmask_b32_e64 v17, v30, -v30, s[10:11]
	v_cndmask_b32_e64 v16, v24, -v24, s[10:11]
	v_pk_fma_f32 v[14:15], v[18:19], v[0:1], v[14:15]
	v_lshlrev_b32_e32 v0, 16, v2
	v_and_b32_e32 v1, 0xffff0000, v2
	v_pk_mul_f32 v[4:5], v[16:17], v[4:5]
	v_cndmask_b32_e64 v17, v31, -v31, s[10:11]
	v_pk_fma_f32 v[4:5], v[8:9], v[0:1], v[4:5]
	v_lshlrev_b32_e32 v8, 16, v3
	v_and_b32_e32 v9, 0xffff0000, v3
	ds_read_b128 v[216:219], v149
	ds_read_b128 v[220:223], v149 offset:32
	ds_read_b128 v[224:227], v149 offset:64
	ds_read_b128 v[228:231], v149 offset:96
	ds_read_b128 v[232:235], v149 offset:4608
	ds_read_b128 v[236:239], v149 offset:4640
	ds_read_b128 v[240:243], v149 offset:4672
	ds_read_b128 v[244:247], v149 offset:4704
	v_cndmask_b32_e64 v16, v25, -v25, s[10:11]
	v_pk_mul_f32 v[6:7], v[16:17], v[6:7]
	v_cvt_pk_bf16_f32 v124, v12, v13
	v_pk_fma_f32 v[6:7], v[10:11], v[8:9], v[6:7]
	v_cvt_pk_bf16_f32 v125, v14, v15
	v_cvt_pk_bf16_f32 v126, v4, v5
	v_cvt_pk_bf16_f32 v127, v6, v7
	v_add_u32_e32 v63, 0x2000, v161
	s_waitcnt lgkmcnt(7)
	v_mfma_f32_32x32x16_bf16 v[0:15], v[216:219], v[124:127], 0
	v_add_u32_e32 v176, 0x3000, v161
	s_waitcnt lgkmcnt(6)
	v_mfma_f32_32x32x16_bf16 v[0:15], v[220:223], v[120:123], v[0:15]
	s_waitcnt lgkmcnt(5)
	v_mfma_f32_32x32x16_bf16 v[0:15], v[224:227], v[116:119], v[0:15]
	s_waitcnt lgkmcnt(4)
	v_mfma_f32_32x32x16_bf16 v[0:15], v[228:231], v[112:115], v[0:15]
	s_waitcnt lgkmcnt(3)
	v_mfma_f32_32x32x16_bf16 v[30:45], v[232:235], v[124:127], 0
	s_waitcnt lgkmcnt(2)
	v_mfma_f32_32x32x16_bf16 v[30:45], v[236:239], v[120:123], v[30:45]
	s_waitcnt lgkmcnt(1)
	v_mfma_f32_32x32x16_bf16 v[30:45], v[240:243], v[116:119], v[30:45]
	s_nop 1
	v_max3_f32 v16, v0, s6, v1
	v_max3_f32 v16, v16, v2, v3
	v_max3_f32 v16, v16, v4, v5
	v_max3_f32 v16, v16, v6, v7
	v_max3_f32 v16, v16, v8, v9
	v_max3_f32 v16, v16, v10, v11
	v_max3_f32 v16, v16, v12, v13
	s_waitcnt lgkmcnt(0)
	v_mfma_f32_32x32x16_bf16 v[30:45], v[244:247], v[112:115], v[30:45]
	v_max3_f32 v16, v16, v14, v15
	s_nop 10
	v_max3_f32 v16, v16, v30, v31
	v_max3_f32 v16, v16, v32, v33
	v_max3_f32 v16, v16, v34, v35
	v_max3_f32 v16, v16, v36, v37
	v_max3_f32 v16, v16, v38, v39
	v_max3_f32 v16, v16, v40, v41
	v_max3_f32 v16, v16, v42, v43
	v_max3_f32 v16, v16, v44, v45
	v_mul_f32_e32 v16, 0x3e38aa3b, v16
	v_mov_b32_e32 v17, v16
	s_nop 1
	v_permlane32_swap_b32_e32 v16, v17
	v_max3_f32 v155, v16, v17, s6
	v_cmp_lt_f32_e32 vcc, s7, v155
	v_sub_f32_e32 v16, 0xf149f2ca, v155
	s_nop 0
	v_cndmask_b32_e64 v62, v163, -v155, vcc
	v_fmamk_f32 v0, v0, 0x3e38aa3b, v62
	v_exp_f32_e32 v128, v0
	v_fmamk_f32 v0, v1, 0x3e38aa3b, v62
	v_exp_f32_e32 v129, v0
	v_fmamk_f32 v0, v2, 0x3e38aa3b, v62
	v_exp_f32_e32 v130, v0
	v_fmamk_f32 v0, v3, 0x3e38aa3b, v62
	v_exp_f32_e32 v131, v0
	v_fmamk_f32 v0, v4, 0x3e38aa3b, v62
	v_exp_f32_e32 v132, v0
	v_fmamk_f32 v0, v5, 0x3e38aa3b, v62
	v_exp_f32_e32 v133, v0
	v_fmamk_f32 v0, v6, 0x3e38aa3b, v62
	v_exp_f32_e32 v134, v0
	v_fmamk_f32 v0, v7, 0x3e38aa3b, v62
	v_exp_f32_e32 v135, v0
	v_fmamk_f32 v0, v8, 0x3e38aa3b, v62
	v_exp_f32_e32 v136, v0
	v_fmamk_f32 v0, v9, 0x3e38aa3b, v62
	v_exp_f32_e32 v158, v0
	v_fmamk_f32 v0, v10, 0x3e38aa3b, v62
	v_exp_f32_e32 v168, v0
	v_fmamk_f32 v0, v11, 0x3e38aa3b, v62
	v_exp_f32_e32 v169, v0
	v_fmamk_f32 v0, v12, 0x3e38aa3b, v62
	v_exp_f32_e32 v170, v0
	v_fmamk_f32 v0, v13, 0x3e38aa3b, v62
	v_exp_f32_e32 v171, v0
	v_fmamk_f32 v0, v14, 0x3e38aa3b, v62
	v_exp_f32_e32 v172, v0
	v_fmamk_f32 v0, v15, 0x3e38aa3b, v62
	v_cvt_pk_bf16_f32 v46, v128, v129
	v_cvt_pk_bf16_f32 v47, v130, v131
	v_cvt_pk_bf16_f32 v48, v132, v133
	v_cvt_pk_bf16_f32 v49, v134, v135
	s_nop 1
	ds_read2_b64 v[50:53], v63 offset0:128 offset1:130
	v_exp_f32_e32 v173, v0
	v_fmamk_f32 v0, v30, 0x3e38aa3b, v62
	ds_read2_b64 v[54:57], v176 offset0:192 offset1:194
	v_exp_f32_e32 v174, v0
	v_exp_f32_e32 v0, v16
	v_fmamk_f32 v32, v32, 0x3e38aa3b, v62
	v_cmp_lt_f32_e32 vcc, s6, v155
	v_exp_f32_e32 v177, v32
	v_fmamk_f32 v32, v33, 0x3e38aa3b, v62
	s_cmp_lg_u64 vcc, 0
	v_exp_f32_e32 v178, v32
	v_fmamk_f32 v32, v34, 0x3e38aa3b, v62
	v_mul_f32_e32 v157, 0, v0
	s_cselect_b64 vcc, -1, 0
	v_exp_f32_e32 v179, v32
	v_fmamk_f32 v32, v35, 0x3e38aa3b, v62
	v_fmamk_f32 v1, v31, 0x3e38aa3b, v62
	v_cndmask_b32_e32 v0, 0, v157, vcc
	v_exp_f32_e32 v180, v32
	v_fmamk_f32 v32, v36, 0x3e38aa3b, v62
	v_exp_f32_e32 v175, v1
	v_mov_b32_e32 v1, v0
	v_mov_b32_e32 v2, v0
	v_mov_b32_e32 v3, v0
	v_mov_b32_e32 v4, v0
	v_mov_b32_e32 v5, v0
	v_mov_b32_e32 v6, v0
	v_mov_b32_e32 v7, v0
	v_mov_b32_e32 v8, v0
	v_mov_b32_e32 v9, v0
	v_mov_b32_e32 v10, v0
	v_mov_b32_e32 v11, v0
	v_mov_b32_e32 v12, v0
	v_mov_b32_e32 v13, v0
	v_mov_b32_e32 v14, v0
	v_mov_b32_e32 v15, v0
	v_exp_f32_e32 v181, v32
	v_fmamk_f32 v32, v37, 0x3e38aa3b, v62
	s_waitcnt lgkmcnt(1)
; #define MFMA32(a, b, c) __builtin_amdgcn_mfma_f32_32x32x16_bf16((a), (b), (c), 0, 0, 0)
; DI void qk_tile(const u16* Ks, const bf16x8* qf, f32x16* s, int rl, int hh) {
; #pragma unroll
;   for (int kb = 0; kb < 2; ++kb) {
; #pragma unroll
;     for (int i = 0; i < 16; ++i) s[kb][i] = 0.f;
; #pragma unroll
;     for (int ks = 0; ks < 4; ++ks) {
;       bf16x8 a = *(const bf16x8*)(Ks + (kb * 32 + rl) * KVS + ks * 16 + hh * 8);
;       s[kb] = MFMA32(a, qf[ks], s[kb]);
;     }
;   }
; }
; DI void pv_tile(const u16* Vs, const f32x16* s, f32x16* o, int rl, int hh) {
; #pragma unroll
;   for (int kk = 0; kk < 4; ++kk) {
;     const int kb = kk >> 1, i0 = 8 * (kk & 1);
;     bf16x8 pf = pack8(s[kb][i0], s[kb][i0 + 1], s[kb][i0 + 2], s[kb][i0 + 3], s[kb][i0 + 4], s[kb][i0 + 5], s[kb][i0 + 6], s[kb][i0 + 7]);
; #pragma unroll
;     for (int db = 0; db < 2; ++db) {
;       const u16* vp = Vs + (db * 32 + rl) * KVS + kk * 16 + hh * 4;
;       s16x4 lo = *(const s16x4*)vp, hi = *(const s16x4*)(vp + 8);
;       bf16x8 a = __builtin_shufflevector(lo, hi, 0, 1, 2, 3, 4, 5, 6, 7);
;       o[db] = MFMA32(a, pf, o[db]);
;     }
;   }
; }
; DI float fexp2(float x) { return __builtin_amdgcn_exp2f(x); }
; template <int MODE>
; DI void osm(f32x16* s, uint32_t vm, float& m, float& l, f32x16* o) {
;   float mx = -1e30f;
; #pragma unroll
;   for (int kb = 0; kb < 2; ++kb)
; #pragma unroll
;     for (int i = 0; i < 16; ++i) {
;       if (MODE == 2) s[kb][i] = ((vm >> (kb * 16 + i)) & 1u) ? s[kb][i] : -1e30f;
;       mx = fmaxf(mx, s[kb][i]);
;     }
;   mx *= SCL2;
;   if (MODE == 1) mx = vm ? mx : -1e30f;
;   mx = xmax32(mx);
;   const float mn = fmaxf(m, mx);
;   const float alpha = fexp2(m - mn);
;   const bool rowok = (MODE == 1) ? (vm != 0u) : true;
;   const float mu = (rowok && mn > -1e29f) ? mn : 1e30f;
;   float rs = 0.f;
; #pragma unroll
;   for (int kb = 0; kb < 2; ++kb)
; #pragma unroll
;     for (int i = 0; i < 16; ++i) {
;       const float pv = fexp2(__builtin_fmaf(s[kb][i], SCL2, -mu));
;       s[kb][i] = pv;
;       rs += pv;
;     }
;   rs = xsum32(rs);
	v_mfma_f32_32x32x16_bf16 v[16:31], v[50:53], v[46:49], v[0:15]
	v_cvt_pk_bf16_f32 v50, v136, v158
	v_cvt_pk_bf16_f32 v51, v168, v169
	v_cvt_pk_bf16_f32 v52, v170, v171
	v_cvt_pk_bf16_f32 v53, v172, v173
	s_nop 1
	v_exp_f32_e32 v182, v32
	ds_read2_b64 v[32:35], v176 offset0:196 offset1:198
	ds_read2_b64 v[58:61], v63 offset0:132 offset1:134
	v_fmamk_f32 v36, v38, 0x3e38aa3b, v62
	v_exp_f32_e32 v183, v36
	v_fmamk_f32 v36, v39, 0x3e38aa3b, v62
	s_waitcnt lgkmcnt(2)
	v_mfma_f32_32x32x16_bf16 v[0:15], v[54:57], v[46:49], v[0:15]
	v_exp_f32_e32 v184, v36
	v_cvt_pk_bf16_f32 v36, v174, v175
	v_cvt_pk_bf16_f32 v37, v177, v178
	v_cvt_pk_bf16_f32 v38, v179, v180
	v_cvt_pk_bf16_f32 v39, v181, v182
	s_nop 1
	ds_read2_b64 v[46:49], v63 offset0:136 offset1:138
	v_fmamk_f32 v40, v40, 0x3e38aa3b, v62
	v_exp_f32_e32 v185, v40
	v_fmamk_f32 v40, v43, 0x3e38aa3b, v62
	v_exp_f32_e32 v188, v40
	s_waitcnt lgkmcnt(2)
	v_mfma_f32_32x32x16_bf16 v[0:15], v[32:35], v[50:53], v[0:15]
	v_fmamk_f32 v32, v41, 0x3e38aa3b, v62
	v_exp_f32_e32 v186, v32
	v_fmamk_f32 v32, v42, 0x3e38aa3b, v62
	v_exp_f32_e32 v187, v32
	ds_read2_b64 v[32:35], v176 offset0:200 offset1:202
	v_fmamk_f32 v40, v44, 0x3e38aa3b, v62
	v_fmac_f32_e32 v62, 0x3e38aa3b, v45
	s_waitcnt lgkmcnt(2)
	v_mfma_f32_32x32x16_bf16 v[16:31], v[58:61], v[50:53], v[16:31]
	v_exp_f32_e32 v189, v40
	v_exp_f32_e32 v190, v62
	s_waitcnt lgkmcnt(1)
	v_mfma_f32_32x32x16_bf16 v[16:31], v[46:49], v[36:39], v[16:31]
	s_waitcnt lgkmcnt(0)
	v_mfma_f32_32x32x16_bf16 v[0:15], v[32:35], v[36:39], v[0:15]
	v_cvt_pk_bf16_f32 v32, v183, v184
	v_cvt_pk_bf16_f32 v33, v185, v186
	v_cvt_pk_bf16_f32 v34, v187, v188
	v_cvt_pk_bf16_f32 v35, v189, v190
	s_nop 1
	ds_read2_b64 v[36:39], v63 offset0:140 offset1:142
	s_waitcnt lgkmcnt(0)
	v_mfma_f32_32x32x16_bf16 v[16:31], v[36:39], v[32:35], v[16:31]
	ds_read2_b64 v[36:39], v176 offset0:204 offset1:206
	s_waitcnt lgkmcnt(0)
	v_mfma_f32_32x32x16_bf16 v[0:15], v[36:39], v[32:35], v[0:15]
	ds_read_b128 v[216:219], v149 offset:18432
	ds_read_b128 v[220:223], v149 offset:18464
	ds_read_b128 v[224:227], v149 offset:18496
	ds_read_b128 v[228:231], v149 offset:18528
	ds_read_b128 v[232:235], v149 offset:23040
	ds_read_b128 v[236:239], v149 offset:23072
	ds_read_b128 v[240:243], v149 offset:23104
	ds_read_b128 v[244:247], v149 offset:23136
	s_waitcnt lgkmcnt(7)
	v_mfma_f32_32x32x16_bf16 v[48:63], v[216:219], v[124:127], 0
	s_waitcnt lgkmcnt(6)
	v_mfma_f32_32x32x16_bf16 v[48:63], v[220:223], v[120:123], v[48:63]
	v_add_f32_e32 v36, 0, v128
	v_add_f32_e32 v36, v129, v36
	v_add_f32_e32 v36, v130, v36
	v_add_f32_e32 v40, v131, v36
	s_waitcnt lgkmcnt(5)
	v_mfma_f32_32x32x16_bf16 v[48:63], v[224:227], v[116:119], v[48:63]
	v_add_f32_e32 v32, v132, v40
	v_add_f32_e32 v32, v133, v32
	v_add_f32_e32 v32, v134, v32
	v_add_f32_e32 v32, v135, v32
	v_add_f32_e32 v32, v136, v32
	v_add_f32_e32 v40, v158, v32
	s_waitcnt lgkmcnt(4)
	v_mfma_f32_32x32x16_bf16 v[48:63], v[228:231], v[112:115], v[48:63]
	v_add_f32_e32 v36, v168, v40
	v_add_f32_e32 v36, v169, v36
	v_add_f32_e32 v36, v170, v36
	v_add_f32_e32 v36, v171, v36
	v_add_f32_e32 v36, v172, v36
	v_add_f32_e32 v132, v173, v36
	v_add_f32_e32 v132, v174, v132
	s_waitcnt lgkmcnt(3)
	v_mfma_f32_32x32x16_bf16 v[32:47], v[232:235], v[124:127], 0
	v_add_f32_e32 v132, v175, v132
	v_add_f32_e32 v132, v177, v132
	v_add_f32_e32 v132, v178, v132
	v_add_f32_e32 v132, v179, v132
	v_add_f32_e32 v136, v180, v132
	s_waitcnt lgkmcnt(2)
	v_mfma_f32_32x32x16_bf16 v[32:47], v[236:239], v[120:123], v[32:47]
	v_add_f32_e32 v128, v181, v136
	v_add_f32_e32 v128, v182, v128
	v_add_f32_e32 v128, v183, v128
	v_add_f32_e32 v128, v184, v128
	v_add_f32_e32 v128, v185, v128
	v_add_f32_e32 v136, v186, v128
	s_waitcnt lgkmcnt(1)
	v_mfma_f32_32x32x16_bf16 v[32:47], v[240:243], v[116:119], v[32:47]
	v_add_f32_e32 v132, v187, v136
	v_add_f32_e32 v132, v188, v132
	v_add_f32_e32 v132, v189, v132
	v_add_f32_e32 v168, v190, v132
	v_mov_b32_e32 v169, v168
	s_nop 1
	v_permlane32_swap_b32_e32 v168, v169
	s_waitcnt lgkmcnt(0)
	v_mfma_f32_32x32x16_bf16 v[32:47], v[244:247], v[112:115], v[32:47]
	v_max3_f32 v128, v48, s6, v49
	v_max3_f32 v128, v128, v50, v51
	v_max3_f32 v128, v128, v52, v53
	v_max3_f32 v128, v128, v54, v55
	v_max3_f32 v128, v128, v56, v57
	v_max3_f32 v128, v128, v58, v59
	v_max3_f32 v128, v128, v60, v61
	v_max3_f32 v128, v128, v62, v63
	s_nop 3
	v_max3_f32 v128, v128, v32, v33
	v_max3_f32 v128, v128, v34, v35
	v_max3_f32 v128, v128, v36, v37
	v_max3_f32 v128, v128, v38, v39
	v_max3_f32 v128, v128, v40, v41
	v_max3_f32 v128, v128, v42, v43
	v_max3_f32 v128, v128, v44, v45
	v_max3_f32 v128, v128, v46, v47
	v_mul_f32_e32 v128, 0x3e38aa3b, v128
	v_mov_b32_e32 v129, v128
	s_nop 1
	v_permlane32_swap_b32_e32 v128, v129
	v_max3_f32 v128, v155, v128, v129
	v_cmp_lt_f32_e32 vcc, s7, v128
	v_sub_f32_e32 v158, v155, v128
	v_exp_f32_e32 v158, v158
	v_cndmask_b32_e64 v170, v163, -v128, vcc
	v_fmamk_f32 v48, v48, 0x3e38aa3b, v170
	v_exp_f32_e32 v129, v48
	v_fmamk_f32 v48, v49, 0x3e38aa3b, v170
	v_exp_f32_e32 v130, v48
	v_fmamk_f32 v48, v50, 0x3e38aa3b, v170
	v_exp_f32_e32 v131, v48
	v_fmamk_f32 v48, v51, 0x3e38aa3b, v170
	v_exp_f32_e32 v132, v48
	v_fmamk_f32 v49, v52, 0x3e38aa3b, v170
	v_add_f32_e32 v48, 0, v129
	v_exp_f32_e32 v133, v49
	v_fmamk_f32 v49, v53, 0x3e38aa3b, v170
	v_add_f32_e32 v48, v130, v48
	v_exp_f32_e32 v134, v49
	v_fmamk_f32 v49, v54, 0x3e38aa3b, v170
	v_add_f32_e32 v48, v131, v48
	v_exp_f32_e32 v135, v49
	v_fmamk_f32 v49, v55, 0x3e38aa3b, v170
	v_add_f32_e32 v48, v132, v48
	v_exp_f32_e32 v136, v49
	v_fmamk_f32 v49, v56, 0x3e38aa3b, v170
	v_add_f32_e32 v48, v133, v48
	v_exp_f32_e32 v49, v49
; #define MFMA32(a, b, c) __builtin_amdgcn_mfma_f32_32x32x16_bf16((a), (b), (c), 0, 0, 0)
; DI float fexp2(float x) { return __builtin_amdgcn_exp2f(x); }
; DI void pv_tile(const u16* Vs, const f32x16* s, f32x16* o, int rl, int hh) {
; #pragma unroll
;   for (int kk = 0; kk < 4; ++kk) {
;     const int kb = kk >> 1, i0 = 8 * (kk & 1);
;     bf16x8 pf = pack8(s[kb][i0], s[kb][i0 + 1], s[kb][i0 + 2], s[kb][i0 + 3], s[kb][i0 + 4], s[kb][i0 + 5], s[kb][i0 + 6], s[kb][i0 + 7]);
; #pragma unroll
;     for (int db = 0; db < 2; ++db) {
;       const u16* vp = Vs + (db * 32 + rl) * KVS + kk * 16 + hh * 4;
;       s16x4 lo = *(const s16x4*)vp, hi = *(const s16x4*)(vp + 8);
;       bf16x8 a = __builtin_shufflevector(lo, hi, 0, 1, 2, 3, 4, 5, 6, 7);
;       o[db] = MFMA32(a, pf, o[db]);
;     }
;   }
; }
; template <int MODE>
; DI void osm(f32x16* s, uint32_t vm, float& m, float& l, f32x16* o) {
;     ...
;   const float mu = (rowok && mn > -1e29f) ? mn : 1e30f;
;   float rs = 0.f;
; #pragma unroll
;   for (int kb = 0; kb < 2; ++kb)
; #pragma unroll
;     for (int i = 0; i < 16; ++i) {
;       const float pv = fexp2(__builtin_fmaf(s[kb][i], SCL2, -mu));
;       s[kb][i] = pv;
;       rs += pv;
;     }
;   rs = xsum32(rs);
;   l = l * alpha + rs;
;   if (__ballot(mn > m) != 0ull) {
; #pragma unroll
;     for (int db = 0; db < 2; ++db)
; #pragma unroll
;       for (int i = 0; i < 16; ++i) o[db][i] *= alpha;
;   }
;   m = mn;
; }
	v_fmamk_f32 v50, v57, 0x3e38aa3b, v170
	v_add_f32_e32 v48, v134, v48
	v_exp_f32_e32 v51, v50
	v_fmamk_f32 v50, v58, 0x3e38aa3b, v170
	v_add_f32_e32 v48, v135, v48
	v_exp_f32_e32 v53, v50
	v_fmamk_f32 v50, v59, 0x3e38aa3b, v170
	v_add_f32_e32 v48, v136, v48
	v_exp_f32_e32 v55, v50
	v_fmamk_f32 v50, v60, 0x3e38aa3b, v170
	v_add_f32_e32 v48, v49, v48
	v_exp_f32_e32 v57, v50
	v_fmamk_f32 v50, v61, 0x3e38aa3b, v170
	v_add_f32_e32 v48, v51, v48
	v_exp_f32_e32 v59, v50
	v_fmamk_f32 v50, v62, 0x3e38aa3b, v170
	v_add_f32_e32 v48, v53, v48
	v_exp_f32_e32 v61, v50
	v_fmamk_f32 v50, v63, 0x3e38aa3b, v170
	v_add_f32_e32 v48, v55, v48
	v_exp_f32_e32 v62, v50
	v_add_f32_e32 v48, v57, v48
	v_add_f32_e32 v48, v59, v48
	v_add_f32_e32 v48, v61, v48
	v_fmamk_f32 v32, v32, 0x3e38aa3b, v170
	v_add_f32_e32 v56, v62, v48
	v_exp_f32_e32 v48, v32
	v_fmamk_f32 v32, v33, 0x3e38aa3b, v170
	v_exp_f32_e32 v50, v32
	v_fmamk_f32 v32, v34, 0x3e38aa3b, v170
	v_exp_f32_e32 v52, v32
	v_fmamk_f32 v32, v35, 0x3e38aa3b, v170
	v_exp_f32_e32 v54, v32
	v_fmamk_f32 v33, v36, 0x3e38aa3b, v170
	v_add_f32_e32 v32, v48, v56
	v_exp_f32_e32 v56, v33
	v_fmamk_f32 v33, v37, 0x3e38aa3b, v170
	v_add_f32_e32 v32, v50, v32
	v_exp_f32_e32 v58, v33
	v_fmamk_f32 v33, v38, 0x3e38aa3b, v170
	v_add_f32_e32 v32, v52, v32
	v_exp_f32_e32 v60, v33
	v_fmamk_f32 v33, v39, 0x3e38aa3b, v170
	v_add_f32_e32 v32, v54, v32
	v_exp_f32_e32 v39, v33
	v_add_f32_e32 v32, v56, v32
	v_add_f32_e32 v32, v58, v32
	v_add_f32_e32 v32, v60, v32
	v_add_f32_e32 v36, v39, v32
	v_fmamk_f32 v32, v40, 0x3e38aa3b, v170
	v_exp_f32_e32 v32, v32
	v_fmamk_f32 v33, v41, 0x3e38aa3b, v170
	v_exp_f32_e32 v33, v33
	v_fmamk_f32 v34, v42, 0x3e38aa3b, v170
	v_exp_f32_e32 v34, v34
	v_fmamk_f32 v35, v43, 0x3e38aa3b, v170
	v_exp_f32_e32 v35, v35
	v_add_f32_e32 v36, v32, v36
	v_add_f32_e32 v36, v33, v36
	v_add_f32_e32 v36, v34, v36
	v_add_f32_e32 v41, v35, v36
	v_fmamk_f32 v36, v44, 0x3e38aa3b, v170
	v_exp_f32_e32 v36, v36
	v_fmamk_f32 v37, v45, 0x3e38aa3b, v170
	v_exp_f32_e32 v37, v37
	v_fmamk_f32 v38, v46, 0x3e38aa3b, v170
	v_exp_f32_e32 v38, v38
	v_fmac_f32_e32 v170, 0x3e38aa3b, v47
	v_exp_f32_e32 v40, v170
	v_add_f32_e32 v41, v36, v41
	v_add_f32_e32 v41, v37, v41
	v_add_f32_e32 v41, v38, v41
	v_add_f32_e32 v170, v40, v41
	v_mov_b32_e32 v171, v170
	s_nop 1
	v_permlane32_swap_b32_e32 v170, v171
	v_cmp_gt_f32_e32 vcc, v128, v155
	s_cbranch_vccz .LBB0_746
	v_pk_mul_f32 v[14:15], v[14:15], v[158:159] op_sel_hi:[1,0]
	v_pk_mul_f32 v[12:13], v[12:13], v[158:159] op_sel_hi:[1,0]
	v_pk_mul_f32 v[10:11], v[10:11], v[158:159] op_sel_hi:[1,0]
	v_pk_mul_f32 v[8:9], v[8:9], v[158:159] op_sel_hi:[1,0]
	v_pk_mul_f32 v[6:7], v[6:7], v[158:159] op_sel_hi:[1,0]
	v_pk_mul_f32 v[4:5], v[4:5], v[158:159] op_sel_hi:[1,0]
	v_pk_mul_f32 v[2:3], v[2:3], v[158:159] op_sel_hi:[1,0]
	v_pk_mul_f32 v[0:1], v[0:1], v[158:159] op_sel_hi:[1,0]
	v_pk_mul_f32 v[30:31], v[30:31], v[158:159] op_sel_hi:[1,0]
	v_pk_mul_f32 v[28:29], v[28:29], v[158:159] op_sel_hi:[1,0]
	v_pk_mul_f32 v[26:27], v[26:27], v[158:159] op_sel_hi:[1,0]
	v_pk_mul_f32 v[24:25], v[24:25], v[158:159] op_sel_hi:[1,0]
	v_pk_mul_f32 v[22:23], v[22:23], v[158:159] op_sel_hi:[1,0]
	v_pk_mul_f32 v[20:21], v[20:21], v[158:159] op_sel_hi:[1,0]
	v_pk_mul_f32 v[18:19], v[18:19], v[158:159] op_sel_hi:[1,0]
	v_pk_mul_f32 v[16:17], v[16:17], v[158:159] op_sel_hi:[1,0]
.LBB0_746:
	v_add_u32_e32 v41, 0x6800, v161
	v_add_u32_e32 v63, 0x7800, v161
	ds_read2_b64 v[216:219], v41 offset0:128 offset1:130
	ds_read2_b64 v[220:223], v63 offset0:192 offset1:194
	ds_read2_b64 v[224:227], v41 offset0:132 offset1:134
	ds_read2_b64 v[228:231], v63 offset0:196 offset1:198
	ds_read2_b64 v[232:235], v41 offset0:136 offset1:138
	ds_read2_b64 v[236:239], v63 offset0:200 offset1:202
	ds_read2_b64 v[240:243], v41 offset0:140 offset1:142
	ds_read2_b64 v[244:247], v63 offset0:204 offset1:206
	s_andn2_b64 vcc, exec, s[16:17]
	v_cvt_pk_bf16_f32 v42, v129, v130
	v_cvt_pk_bf16_f32 v43, v131, v132
	v_cvt_pk_bf16_f32 v44, v133, v134
	v_cvt_pk_bf16_f32 v45, v135, v136
	s_nop 1
	s_waitcnt lgkmcnt(7)
	v_mfma_f32_32x32x16_bf16 v[16:31], v[216:219], v[42:45], v[16:31]
	s_waitcnt lgkmcnt(6)
	v_mfma_f32_32x32x16_bf16 v[0:15], v[220:223], v[42:45], v[0:15]
	v_cvt_pk_bf16_f32 v42, v49, v51
	v_cvt_pk_bf16_f32 v43, v53, v55
	v_cvt_pk_bf16_f32 v44, v57, v59
	v_cvt_pk_bf16_f32 v45, v61, v62
	s_nop 1
	s_waitcnt lgkmcnt(5)
	v_mfma_f32_32x32x16_bf16 v[16:31], v[224:227], v[42:45], v[16:31]
	s_waitcnt lgkmcnt(4)
	v_mfma_f32_32x32x16_bf16 v[0:15], v[228:231], v[42:45], v[0:15]
	v_cvt_pk_bf16_f32 v42, v48, v50
	v_cvt_pk_bf16_f32 v43, v52, v54
	v_cvt_pk_bf16_f32 v44, v56, v58
	v_cvt_pk_bf16_f32 v45, v60, v39
	s_nop 1
	s_waitcnt lgkmcnt(3)
	v_mfma_f32_32x32x16_bf16 v[16:31], v[232:235], v[42:45], v[16:31]
	s_waitcnt lgkmcnt(2)
	v_mfma_f32_32x32x16_bf16 v[0:15], v[236:239], v[42:45], v[0:15]
	v_cvt_pk_bf16_f32 v42, v32, v33
	v_cvt_pk_bf16_f32 v43, v34, v35
	v_cvt_pk_bf16_f32 v44, v36, v37
	v_cvt_pk_bf16_f32 v45, v38, v40
	s_nop 1
	s_waitcnt lgkmcnt(1)
	v_mfma_f32_32x32x16_bf16 v[16:31], v[240:243], v[42:45], v[16:31]
	s_waitcnt lgkmcnt(0)
	v_mfma_f32_32x32x16_bf16 v[0:15], v[244:247], v[42:45], v[0:15]
	s_cbranch_vccnz .LBB0_748
	s_ashr_i32 s4, s34, 8
	s_ashr_i32 s5, s4, 31
	s_lshl_b64 s[4:5], s[4:5], 13
	s_waitcnt vmcnt(0)
	v_lshrrev_b32_e32 v136, 2, v151
	v_lshl_add_u64 v[32:33], s[4:5], 0, v[136:137]
	v_mov_b64_e32 v[34:35], s[24:25]
	v_mad_u64_u32 v[34:35], s[4:5], v32, s0, v[34:35]
	s_lshl_b32 s4, s34, 2
	v_mad_i32_i24 v35, v33, s0, v35
	s_and_b32 s38, s4, 0x380
	v_lshl_add_u64 v[32:33], v[34:35], 0, s[38:39]
	v_mov_b32_e32 v155, v137
	v_lshl_add_u64 v[32:33], v[32:33], 0, v[154:155]
	global_load_dwordx4 v[64:67], v[32:33], off offset:2048
	global_load_dwordx4 v[68:71], v[32:33], off offset:2080
	global_load_dwordx4 v[72:75], v[32:33], off offset:2112
	global_load_dwordx4 v[76:79], v[32:33], off offset:2144
; #define MFMA32(a, b, c) __builtin_amdgcn_mfma_f32_32x32x16_bf16((a), (b), (c), 0, 0, 0)
; DI float fexp2(float x) { return __builtin_amdgcn_exp2f(x); }
; DI void qk_tile(const u16* Ks, const bf16x8* qf, f32x16* s, int rl, int hh) {
; #pragma unroll
;   for (int kb = 0; kb < 2; ++kb) {
; #pragma unroll
;     for (int i = 0; i < 16; ++i) s[kb][i] = 0.f;
; #pragma unroll
;     for (int ks = 0; ks < 4; ++ks) {
;       bf16x8 a = *(const bf16x8*)(Ks + (kb * 32 + rl) * KVS + ks * 16 + hh * 8);
;       s[kb] = MFMA32(a, qf[ks], s[kb]);
;     }
;   }
; }
; template <int MODE>
; DI void osm(f32x16* s, uint32_t vm, float& m, float& l, f32x16* o) {
;   float mx = -1e30f;
; #pragma unroll
;   for (int kb = 0; kb < 2; ++kb)
; #pragma unroll
;     for (int i = 0; i < 16; ++i) {
;       if (MODE == 2) s[kb][i] = ((vm >> (kb * 16 + i)) & 1u) ? s[kb][i] : -1e30f;
;       mx = fmaxf(mx, s[kb][i]);
;     }
;   mx *= SCL2;
;   if (MODE == 1) mx = vm ? mx : -1e30f;
;   mx = xmax32(mx);
;   const float mn = fmaxf(m, mx);
;   const float alpha = fexp2(m - mn);
;   const bool rowok = (MODE == 1) ? (vm != 0u) : true;
;   const float mu = (rowok && mn > -1e29f) ? mn : 1e30f;
;   float rs = 0.f;
; #pragma unroll
;   for (int kb = 0; kb < 2; ++kb)
; #pragma unroll
;     for (int i = 0; i < 16; ++i) {
;       const float pv = fexp2(__builtin_fmaf(s[kb][i], SCL2, -mu));
;       s[kb][i] = pv;
;       rs += pv;
;     }
;   rs = xsum32(rs);
;   l = l * alpha + rs;
;   if (__ballot(mn > m) != 0ull) {
; #pragma unroll
;     for (int db = 0; db < 2; ++db)
; #pragma unroll
;       for (int i = 0; i < 16; ++i) o[db][i] *= alpha;
;   }
;   m = mn;
; }
.LBB0_748:
	ds_read_b128 v[216:219], v149 offset:36864
	ds_read_b128 v[220:223], v149 offset:36896
	ds_read_b128 v[224:227], v149 offset:36928
	ds_read_b128 v[228:231], v149 offset:36960
	ds_read_b128 v[232:235], v149 offset:41472
	ds_read_b128 v[236:239], v149 offset:41504
	ds_read_b128 v[240:243], v149 offset:41536
	ds_read_b128 v[244:247], v149 offset:41568
	s_waitcnt lgkmcnt(7)
	v_mfma_f32_32x32x16_bf16 v[48:63], v[216:219], v[124:127], 0
	s_waitcnt lgkmcnt(6)
	v_mfma_f32_32x32x16_bf16 v[48:63], v[220:223], v[120:123], v[48:63]
	s_waitcnt lgkmcnt(5)
	v_mfma_f32_32x32x16_bf16 v[48:63], v[224:227], v[116:119], v[48:63]
	s_waitcnt lgkmcnt(4)
	v_mfma_f32_32x32x16_bf16 v[48:63], v[228:231], v[112:115], v[48:63]
	s_waitcnt lgkmcnt(3)
	v_mfma_f32_32x32x16_bf16 v[32:47], v[232:235], v[124:127], 0
	s_nop 9
	v_max3_f32 v129, v48, s6, v49
	v_max3_f32 v129, v129, v50, v51
	v_max3_f32 v129, v129, v52, v53
	v_max3_f32 v129, v129, v54, v55
	v_max3_f32 v129, v129, v56, v57
	v_max3_f32 v129, v129, v58, v59
	v_max3_f32 v129, v129, v60, v61
	s_waitcnt lgkmcnt(2)
	v_mfma_f32_32x32x16_bf16 v[32:47], v[236:239], v[120:123], v[32:47]
	v_max3_f32 v129, v129, v62, v63
	s_waitcnt lgkmcnt(1)
	v_mfma_f32_32x32x16_bf16 v[32:47], v[240:243], v[116:119], v[32:47]
	s_waitcnt lgkmcnt(0)
	v_mfma_f32_32x32x16_bf16 v[32:47], v[244:247], v[112:115], v[32:47]
	s_nop 11
	v_max3_f32 v129, v129, v32, v33
	v_max3_f32 v129, v129, v34, v35
	v_max3_f32 v129, v129, v36, v37
	v_max3_f32 v129, v129, v38, v39
	v_max3_f32 v129, v129, v40, v41
	v_max3_f32 v129, v129, v42, v43
	v_max3_f32 v129, v129, v44, v45
	v_max3_f32 v129, v129, v46, v47
	v_mul_f32_e32 v129, 0x3e38aa3b, v129
	v_mov_b32_e32 v130, v129
	s_nop 1
	v_permlane32_swap_b32_e32 v129, v130
	v_max3_f32 v173, v128, v129, v130
	v_cmp_lt_f32_e32 vcc, s7, v173
	v_sub_f32_e32 v129, v128, v173
	v_exp_f32_e32 v136, v129
	v_cndmask_b32_e64 v130, v163, -v173, vcc
	v_fmamk_f32 v48, v48, 0x3e38aa3b, v130
	v_fmamk_f32 v49, v49, 0x3e38aa3b, v130
	v_exp_f32_e32 v132, v48
	v_fmamk_f32 v50, v50, 0x3e38aa3b, v130
	v_exp_f32_e32 v133, v49
	v_fmamk_f32 v51, v51, 0x3e38aa3b, v130
	v_exp_f32_e32 v134, v50
	v_fmamk_f32 v52, v52, 0x3e38aa3b, v130
	v_exp_f32_e32 v135, v51
	v_fmamk_f32 v53, v53, 0x3e38aa3b, v130
	v_exp_f32_e32 v174, v52
	v_add_f32_e32 v48, 0, v132
	v_fmamk_f32 v54, v54, 0x3e38aa3b, v130
	v_exp_f32_e32 v175, v53
	v_add_f32_e32 v48, v133, v48
	v_fmamk_f32 v55, v55, 0x3e38aa3b, v130
	v_exp_f32_e32 v176, v54
	v_add_f32_e32 v48, v134, v48
	v_fmamk_f32 v56, v56, 0x3e38aa3b, v130
	v_exp_f32_e32 v177, v55
	v_add_f32_e32 v48, v135, v48
	v_fmamk_f32 v57, v57, 0x3e38aa3b, v130
	v_exp_f32_e32 v49, v56
	v_add_f32_e32 v48, v174, v48
	v_fmamk_f32 v58, v58, 0x3e38aa3b, v130
	v_exp_f32_e32 v50, v57
	v_add_f32_e32 v48, v175, v48
	v_fmamk_f32 v59, v59, 0x3e38aa3b, v130
	v_exp_f32_e32 v52, v58
	v_add_f32_e32 v48, v176, v48
	v_fmamk_f32 v60, v60, 0x3e38aa3b, v130
	v_exp_f32_e32 v53, v59
	v_add_f32_e32 v48, v177, v48
	v_fmamk_f32 v61, v61, 0x3e38aa3b, v130
	v_exp_f32_e32 v54, v60
	v_add_f32_e32 v48, v49, v48
	v_add_f32_e32 v48, v50, v48
	v_exp_f32_e32 v59, v61
	v_fmamk_f32 v51, v62, 0x3e38aa3b, v130
	v_add_f32_e32 v48, v52, v48
	v_exp_f32_e32 v61, v51
	v_fmamk_f32 v51, v63, 0x3e38aa3b, v130
	v_add_f32_e32 v48, v53, v48
	v_exp_f32_e32 v62, v51
	v_add_f32_e32 v48, v54, v48
	v_add_f32_e32 v48, v59, v48
	v_add_f32_e32 v48, v61, v48
	v_fmamk_f32 v32, v32, 0x3e38aa3b, v130
	v_add_f32_e32 v57, v62, v48
	v_exp_f32_e32 v48, v32
	v_fmamk_f32 v32, v33, 0x3e38aa3b, v130
	v_exp_f32_e32 v51, v32
	v_fmamk_f32 v32, v34, 0x3e38aa3b, v130
	v_exp_f32_e32 v55, v32
	v_fmamk_f32 v32, v35, 0x3e38aa3b, v130
	v_exp_f32_e32 v56, v32
	v_fmamk_f32 v33, v36, 0x3e38aa3b, v130
	v_add_f32_e32 v32, v48, v57
	v_exp_f32_e32 v57, v33
	v_fmamk_f32 v33, v37, 0x3e38aa3b, v130
	v_add_f32_e32 v32, v51, v32
	v_exp_f32_e32 v58, v33
	v_fmamk_f32 v33, v38, 0x3e38aa3b, v130
	v_add_f32_e32 v32, v55, v32
	v_exp_f32_e32 v60, v33
	v_fmamk_f32 v33, v39, 0x3e38aa3b, v130
	v_add_f32_e32 v32, v56, v32
	v_exp_f32_e32 v39, v33
	v_add_f32_e32 v32, v57, v32
	v_add_f32_e32 v32, v58, v32
	v_add_f32_e32 v32, v60, v32
	v_add_f32_e32 v36, v39, v32
	v_fmamk_f32 v32, v40, 0x3e38aa3b, v130
	v_exp_f32_e32 v32, v32
	v_fmamk_f32 v33, v41, 0x3e38aa3b, v130
	v_exp_f32_e32 v33, v33
	v_fmamk_f32 v34, v42, 0x3e38aa3b, v130
	v_exp_f32_e32 v34, v34
	v_fmamk_f32 v35, v43, 0x3e38aa3b, v130
	v_exp_f32_e32 v35, v35
	v_add_f32_e32 v36, v32, v36
	v_add_f32_e32 v36, v33, v36
	v_add_f32_e32 v36, v34, v36
	v_add_f32_e32 v41, v35, v36
	v_fmamk_f32 v36, v44, 0x3e38aa3b, v130
	v_exp_f32_e32 v36, v36
	v_fmamk_f32 v37, v45, 0x3e38aa3b, v130
	v_exp_f32_e32 v37, v37
	v_fmamk_f32 v38, v46, 0x3e38aa3b, v130
	v_exp_f32_e32 v38, v38
	v_fmac_f32_e32 v130, 0x3e38aa3b, v47
	v_exp_f32_e32 v40, v130
	v_add_f32_e32 v41, v36, v41
	v_add_f32_e32 v41, v37, v41
	v_add_f32_e32 v41, v38, v41
	v_add_f32_e32 v155, v40, v41
	v_mov_b32_e32 v172, v155
	s_nop 1
	v_permlane32_swap_b32_e32 v155, v172
	v_cmp_gt_f32_e32 vcc, v173, v128
	s_cbranch_vccz .LBB0_750
	v_pk_mul_f32 v[14:15], v[14:15], v[136:137] op_sel_hi:[1,0]
	v_pk_mul_f32 v[12:13], v[12:13], v[136:137] op_sel_hi:[1,0]
	v_pk_mul_f32 v[10:11], v[10:11], v[136:137] op_sel_hi:[1,0]
	v_pk_mul_f32 v[8:9], v[8:9], v[136:137] op_sel_hi:[1,0]
	v_pk_mul_f32 v[6:7], v[6:7], v[136:137] op_sel_hi:[1,0]
	v_pk_mul_f32 v[4:5], v[4:5], v[136:137] op_sel_hi:[1,0]
	v_pk_mul_f32 v[2:3], v[2:3], v[136:137] op_sel_hi:[1,0]
	v_pk_mul_f32 v[0:1], v[0:1], v[136:137] op_sel_hi:[1,0]
	v_pk_mul_f32 v[30:31], v[30:31], v[136:137] op_sel_hi:[1,0]
	v_pk_mul_f32 v[28:29], v[28:29], v[136:137] op_sel_hi:[1,0]
	v_pk_mul_f32 v[26:27], v[26:27], v[136:137] op_sel_hi:[1,0]
	v_pk_mul_f32 v[24:25], v[24:25], v[136:137] op_sel_hi:[1,0]
	v_pk_mul_f32 v[22:23], v[22:23], v[136:137] op_sel_hi:[1,0]
	v_pk_mul_f32 v[20:21], v[20:21], v[136:137] op_sel_hi:[1,0]
	v_pk_mul_f32 v[18:19], v[18:19], v[136:137] op_sel_hi:[1,0]
	v_pk_mul_f32 v[16:17], v[16:17], v[136:137] op_sel_hi:[1,0]

; #define MFMA32(a, b, c) __builtin_amdgcn_mfma_f32_32x32x16_bf16((a), (b), (c), 0, 0, 0)
; DI void pv_tile(const u16* Vs, const f32x16* s, f32x16* o, int rl, int hh) {
; #pragma unroll
;   for (int kk = 0; kk < 4; ++kk) {
;     const int kb = kk >> 1, i0 = 8 * (kk & 1);
;     bf16x8 pf = pack8(s[kb][i0], s[kb][i0 + 1], s[kb][i0 + 2], s[kb][i0 + 3], s[kb][i0 + 4], s[kb][i0 + 5], s[kb][i0 + 6], s[kb][i0 + 7]);
; #pragma unroll
;     for (int db = 0; db < 2; ++db) {
;       const u16* vp = Vs + (db * 32 + rl) * KVS + kk * 16 + hh * 4;
;       s16x4 lo = *(const s16x4*)vp, hi = *(const s16x4*)(vp + 8);
;       bf16x8 a = __builtin_shufflevector(lo, hi, 0, 1, 2, 3, 4, 5, 6, 7);
;       o[db] = MFMA32(a, pf, o[db]);
;     }
;   }
; }
; DI void moba_gather_phase(int ws, PP p, char* shm) {
;     ...
;     if (valid) {
;       u16* pe = p->part + (((long)bh * SEQ + tq) * 3 + slot) * 72;
;       store_o(pe + 8, o, 1.f / l, hh);
;       if (hh == 0) { wt32f((float*)pe, m); wt32f((float*)pe + 1, l); }
;     }
.LBB0_752:
	v_add_u32_e32 v43, 0xf800, v161
	ds_read2_b64 v[216:219], v43 offset0:128 offset1:130
	ds_read2_b64 v[220:223], v164 offset0:64 offset1:66
	ds_read2_b64 v[224:227], v43 offset0:132 offset1:134
	ds_read2_b64 v[228:231], v165 offset0:64 offset1:66
	ds_read2_b64 v[232:235], v43 offset0:136 offset1:138
	ds_read2_b64 v[236:239], v166 offset0:64 offset1:66
	ds_read2_b64 v[240:243], v43 offset0:140 offset1:142
	ds_read2_b64 v[244:247], v167 offset0:64 offset1:66
	v_cvt_pk_bf16_f32 v44, v113, v114
	v_cvt_pk_bf16_f32 v45, v115, v116
	v_cvt_pk_bf16_f32 v46, v117, v118
	v_cvt_pk_bf16_f32 v47, v119, v120
	s_nop 1
	s_waitcnt lgkmcnt(7)
	v_mfma_f32_32x32x16_bf16 v[16:31], v[216:219], v[44:47], v[16:31]
	s_waitcnt lgkmcnt(6)
	v_mfma_f32_32x32x16_bf16 v[0:15], v[220:223], v[44:47], v[0:15]
	v_cvt_pk_bf16_f32 v44, v48, v50
	v_cvt_pk_bf16_f32 v45, v52, v54
	v_cvt_pk_bf16_f32 v46, v56, v58
	v_cvt_pk_bf16_f32 v47, v60, v62
	s_nop 1
	s_waitcnt lgkmcnt(5)
	v_mfma_f32_32x32x16_bf16 v[16:31], v[224:227], v[44:47], v[16:31]
	s_waitcnt lgkmcnt(4)
	v_mfma_f32_32x32x16_bf16 v[0:15], v[228:231], v[44:47], v[0:15]
	v_cvt_pk_bf16_f32 v44, v49, v51
	v_cvt_pk_bf16_f32 v45, v53, v55
	v_cvt_pk_bf16_f32 v46, v57, v59
	v_cvt_pk_bf16_f32 v47, v61, v63
	s_nop 1
	s_waitcnt lgkmcnt(3)
	v_mfma_f32_32x32x16_bf16 v[16:31], v[232:235], v[44:47], v[16:31]
	s_waitcnt lgkmcnt(2)
	v_mfma_f32_32x32x16_bf16 v[0:15], v[236:239], v[44:47], v[0:15]
	v_cvt_pk_bf16_f32 v44, v35, v36
	v_cvt_pk_bf16_f32 v45, v37, v38
	v_cvt_pk_bf16_f32 v46, v39, v40
	v_cvt_pk_bf16_f32 v47, v41, v42
	s_nop 1
	s_waitcnt lgkmcnt(1)
	v_mfma_f32_32x32x16_bf16 v[16:31], v[240:243], v[44:47], v[16:31]
	s_waitcnt lgkmcnt(0)
	v_mfma_f32_32x32x16_bf16 v[0:15], v[244:247], v[44:47], v[0:15]
	s_and_saveexec_b64 s[16:17], s[42:43]
	s_cbranch_execz .LBB0_732
	v_add_f32_e32 v35, v168, v169
	v_add_f32_e32 v35, v35, v157
	v_add_f32_e32 v36, v170, v171
	s_load_dwordx2 s[4:5], s[20:21], 0x178
	v_fmac_f32_e32 v36, v35, v158
	v_add_f32_e32 v35, v155, v172
	s_ashr_i32 s41, s40, 31
	v_fmac_f32_e32 v35, v36, v136
	v_add_f32_e32 v113, v33, v34
	s_lshl_b64 s[8:9], s[40:41], 13
	v_mov_b32_e32 v157, v137
	v_fmac_f32_e32 v113, v35, v32
	v_and_b32_e32 v136, 3, v153
	v_lshl_add_u64 v[32:33], s[8:9], 0, v[156:157]
	v_mad_u64_u32 v[34:35], s[8:9], v32, 3, v[136:137]
	v_mad_i32_i24 v35, v33, 3, v35
	s_waitcnt lgkmcnt(0)
	v_mov_b64_e32 v[32:33], s[4:5]
	v_div_scale_f32 v36, s[4:5], v113, v113, 1.0
	v_rcp_f32_e32 v37, v36
	v_mad_u64_u32 v[32:33], s[4:5], v34, s1, v[32:33]
	v_mad_i32_i24 v33, v35, s1, v33
	v_fma_f32 v34, -v36, v37, 1.0
	v_fmac_f32_e32 v37, v34, v37
	v_div_scale_f32 v34, vcc, 1.0, v113, 1.0
	v_mul_f32_e32 v35, v34, v37
	v_fma_f32 v38, -v36, v35, v34
	v_fmac_f32_e32 v35, v38, v37
	v_fma_f32 v34, -v36, v35, v34
	v_div_fmas_f32 v34, v34, v37, v35
	v_div_fixup_f32 v34, v34, v113, 1.0
	v_mov_b32_e32 v153, v137
	v_pk_mul_f32 v[16:17], v[34:35], v[16:17] op_sel_hi:[0,1]
	v_pk_mul_f32 v[18:19], v[34:35], v[18:19] op_sel_hi:[0,1]
	v_pk_mul_f32 v[0:1], v[34:35], v[0:1] op_sel_hi:[0,1]
	v_pk_mul_f32 v[2:3], v[34:35], v[2:3] op_sel_hi:[0,1]
	v_lshl_add_u64 v[36:37], v[32:33], 0, v[152:153]
	v_cvt_pk_bf16_f32 v16, v16, v17
	v_cvt_pk_bf16_f32 v17, v18, v19
	v_cvt_pk_bf16_f32 v0, v0, v1
	v_cvt_pk_bf16_f32 v1, v2, v3
	global_store_dwordx2 v[36:37], v[16:17], off offset:16
	v_pk_mul_f32 v[16:17], v[34:35], v[20:21] op_sel_hi:[0,1]
	v_pk_mul_f32 v[18:19], v[34:35], v[22:23] op_sel_hi:[0,1]
	global_store_dwordx2 v[36:37], v[0:1], off offset:80
	v_pk_mul_f32 v[0:1], v[34:35], v[4:5] op_sel_hi:[0,1]
	v_pk_mul_f32 v[2:3], v[34:35], v[6:7] op_sel_hi:[0,1]
	v_cvt_pk_bf16_f32 v16, v16, v17
	v_cvt_pk_bf16_f32 v17, v18, v19
	v_cvt_pk_bf16_f32 v0, v0, v1
	v_cvt_pk_bf16_f32 v1, v2, v3
	global_store_dwordx2 v[36:37], v[16:17], off offset:32
	v_pk_mul_f32 v[16:17], v[34:35], v[24:25] op_sel_hi:[0,1]
	v_pk_mul_f32 v[18:19], v[34:35], v[26:27] op_sel_hi:[0,1]
	global_store_dwordx2 v[36:37], v[0:1], off offset:96
	v_pk_mul_f32 v[0:1], v[34:35], v[8:9] op_sel_hi:[0,1]
	v_pk_mul_f32 v[2:3], v[34:35], v[10:11] op_sel_hi:[0,1]
	v_cvt_pk_bf16_f32 v16, v16, v17
	v_cvt_pk_bf16_f32 v17, v18, v19
	v_cvt_pk_bf16_f32 v0, v0, v1
	v_cvt_pk_bf16_f32 v1, v2, v3
	global_store_dwordx2 v[36:37], v[16:17], off offset:48
	v_pk_mul_f32 v[16:17], v[34:35], v[28:29] op_sel_hi:[0,1]
	v_pk_mul_f32 v[18:19], v[34:35], v[30:31] op_sel_hi:[0,1]
	global_store_dwordx2 v[36:37], v[0:1], off offset:112
	v_pk_mul_f32 v[0:1], v[34:35], v[12:13] op_sel_hi:[0,1]
	v_pk_mul_f32 v[2:3], v[34:35], v[14:15] op_sel_hi:[0,1]
	v_cvt_pk_bf16_f32 v16, v16, v17
	v_cvt_pk_bf16_f32 v17, v18, v19
	v_cvt_pk_bf16_f32 v0, v0, v1
	v_cvt_pk_bf16_f32 v1, v2, v3
	global_store_dwordx2 v[36:37], v[16:17], off offset:64
	global_store_dwordx2 v[36:37], v[0:1], off offset:128
	s_and_b64 exec, exec, s[10:11]
	s_cbranch_execz .LBB0_732
	global_store_dwordx2 v[32:33], v[112:113], off
	s_branch .LBB0_732
